# v35 + GEMM phase prologue (out-proj/FFN-out and FFN-in): the six tile-1 LDS-DMA loads issued right after the eight tile-0 loads, before the LN-stat block and the first wait
# speedup vs baseline: 1.0187x; 1.0187x over previous
.LBB0_1094:
	s_add_u32 s52, s28, 0x8288000
	s_addc_u32 s53, s29, 0
	s_add_u32 s3, s28, s18
	s_addc_u32 s5, s29, s19
	s_add_u32 s4, s3, 0x2000000
	s_addc_u32 s5, s5, 0
	s_add_u32 s3, s28, s20
	s_addc_u32 s27, s29, s21
	s_add_u32 s46, s3, 0x6218000
	s_addc_u32 s47, s27, 0
	s_add_u32 s48, s3, 0x622e000
	s_addc_u32 s49, s27, 0
	s_add_u32 s50, s28, 0x16a54000
	s_addc_u32 s51, s29, 0
	v_readlane_b32 s28, v254, 25
	v_mov_b32_e32 v18, v213
	v_readlane_b32 s29, v254, 26
	s_waitcnt lgkmcnt(0)
	s_barrier
	s_andn2_b64 vcc, exec, s[28:29]
	v_readfirstlane_b32 s38, v18
	s_cbranch_vccnz .LBB0_1104
	v_lshlrev_b32_e32 v1, 4, v18
	v_add_u32_e32 v2, 0x2000, v1
	v_ashrrev_i32_e32 v3, 31, v2
	v_lshrrev_b32_e32 v3, 22, v3
	v_add_u32_e32 v3, v2, v3
	v_ashrrev_i32_e32 v10, 10, v3
	v_mul_i32_i24_e32 v3, 0x400, v10
	v_sub_u32_e32 v2, v2, v3
	v_lshrrev_b32_e32 v3, 4, v2
	v_bitop3_b32 v2, v3, v2, 32 bitop3:0x6c
	v_ashrrev_i32_e32 v3, 31, v2
	v_lshrrev_b32_e32 v3, 26, v3
	v_add_u32_e32 v3, v2, v3
	v_ashrrev_i32_e32 v11, 6, v3
	v_and_b32_e32 v3, 0xc0, v3
	v_sub_u32_e32 v2, v2, v3
	v_ashrrev_i16_sdwa v2, v219, sext(v2) dst_sel:DWORD dst_unused:UNUSED_PAD src0_sel:DWORD src1_sel:BYTE_0
	v_bfe_i32 v13, v2, 0, 16
	v_bfe_i32 v2, v18, 27, 1
	v_lshrrev_b32_e32 v2, 22, v2
	v_add_u32_e32 v2, v1, v2
	v_and_b32_e32 v2, 0xfffffc00, v2
	v_sub_u32_e32 v1, v1, v2
	v_lshrrev_b32_e32 v2, 4, v1
	v_bitop3_b32 v1, v2, v1, 32 bitop3:0x6c
	v_ashrrev_i32_e32 v3, 31, v18
	v_lshlrev_b32_e32 v4, 3, v10
	v_ashrrev_i32_e32 v2, 31, v1
	v_lshrrev_b32_e32 v3, 26, v3
	v_and_b32_e32 v4, 0x1ffff0, v4
	v_lshlrev_b32_e32 v5, 5, v10
	v_lshrrev_b32_e32 v2, 26, v2
	v_add_u32_e32 v3, v18, v3
	v_add_u32_e32 v4, v11, v4
	v_and_b32_e32 v12, 32, v5
	v_add_u32_e32 v2, v1, v2
	v_ashrrev_i32_e32 v15, 6, v3
	s_ashr_i32 s3, s38, 6
	v_lshl_or_b32 v4, v4, 10, v12
	v_ashrrev_i32_e32 v14, 6, v2
	v_lshlrev_b32_e32 v3, 3, v15
	v_and_b32_e32 v2, 0xc0, v2
	s_ashr_i32 s27, s38, 8
	s_lshl_b32 s68, s3, 10
	v_add_lshl_u32 v162, v4, v13, 1
	v_and_b32_e32 v3, 0x1ffff0, v3
	v_lshlrev_b32_e32 v4, 5, v15
	v_sub_u32_e32 v1, v1, v2
	v_readlane_b32 s28, v252, 53
	v_add_u32_e32 v3, v14, v3
	v_and_b32_e32 v16, 32, v4
	v_ashrrev_i16_sdwa v1, v219, sext(v1) dst_sel:DWORD dst_unused:UNUSED_PAD src0_sel:DWORD src1_sel:BYTE_0
	v_readlane_b32 s29, v252, 54
	s_add_u32 s54, s4, s28
	v_lshl_or_b32 v3, v3, 10, v16
	v_bfe_i32 v17, v1, 0, 16
	s_addc_u32 s55, s5, s29
	s_add_i32 s69, s68, 0
	v_add_lshl_u32 v164, v3, v17, 1
	s_add_i32 m0, s69, 0x10000
	v_readlane_b32 s28, v252, 50
	global_load_lds_dwordx4 v164, s[54:55]
	s_add_i32 m0, s69, 0x12000
	s_add_u32 s56, s52, s28
	global_load_lds_dwordx4 v162, s[54:55]
	s_addc_u32 s57, s53, 0
	s_mov_b32 m0, s69
	s_add_i32 s70, s69, 0x2000
	global_load_lds_dwordx4 v164, s[56:57]
	s_mov_b32 m0, s70
	s_add_u32 s28, s54, 0x40000
	global_load_lds_dwordx4 v162, s[56:57]
	s_addc_u32 s29, s55, 0
	s_add_i32 m0, s69, 0x14000
	v_mov_b32_e32 v165, v0
	global_load_lds_dwordx4 v164, s[28:29]
	s_add_i32 m0, s69, 0x16000
	v_mov_b32_e32 v163, v0
	global_load_lds_dwordx4 v162, s[28:29]
	s_add_u32 s28, s56, 0x40000
	s_addc_u32 s29, s57, 0
	s_add_i32 s71, s69, 0x4000
	s_mov_b32 m0, s71
	s_add_i32 s72, s69, 0x6000
	global_load_lds_dwordx4 v164, s[28:29]
	s_mov_b32 m0, s72
	v_lshl_add_u64 v[8:9], s[54:55], 0, v[164:165]
	global_load_lds_dwordx4 v162, s[28:29]
	s_add_u32 s98, s54, s22
	s_addc_u32 s99, s55, s23
	s_add_i32 m0, s69, 0x18000
	s_nop 0
	global_load_lds_dwordx4 v164, s[98:99]
	s_add_i32 m0, s69, 0x1a000
	s_nop 0
	global_load_lds_dwordx4 v162, s[98:99]
	s_add_u32 s100, s56, s22
	s_addc_u32 s101, s57, s23
	s_add_i32 m0, s69, 0x8000
	s_nop 0
	global_load_lds_dwordx4 v164, s[100:101]
	s_add_i32 m0, s69, 0xa000
	s_nop 0
	global_load_lds_dwordx4 v162, s[100:101]
	s_add_u32 s98, s54, 0x40080
	s_addc_u32 s99, s55, 0
	s_add_i32 m0, s69, 0x1c000
	s_nop 0
	global_load_lds_dwordx4 v164, s[98:99]
	s_add_i32 m0, s69, 0x1e000
	s_nop 0
	global_load_lds_dwordx4 v162, s[98:99]
	s_mov_b64 s[100:101], exec
	v_readlane_b32 s98, v254, 59
	v_readlane_b32 s99, v254, 60
	s_and_b64 s[98:99], s[100:101], s[98:99]
	s_mov_b64 exec, s[98:99]
	s_cbranch_execz .Lstat_skip_3
	v_lshl_add_u64 v[134:135], s[42:43], 0, v[198:199]
	global_load_dwordx4 v[100:103], v[134:135], off
	global_load_dwordx4 v[104:107], v[134:135], off offset:16
	global_load_dwordx4 v[108:111], v[134:135], off offset:32
	global_load_dwordx4 v[112:115], v[134:135], off offset:48
	global_load_dwordx4 v[116:119], v[134:135], off offset:64
	global_load_dwordx4 v[120:123], v[134:135], off offset:80
	global_load_dwordx4 v[124:127], v[134:135], off offset:96
	global_load_dwordx4 v[128:131], v[134:135], off offset:112
	s_mov_b32 s98, 0x3a800000
	s_waitcnt vmcnt(0) lgkmcnt(0)
	v_pk_add_f32 v[100:101], v[100:101], v[102:103]
	v_pk_add_f32 v[104:105], v[104:105], v[106:107]
	v_pk_add_f32 v[108:109], v[108:109], v[110:111]
	v_pk_add_f32 v[112:113], v[112:113], v[114:115]
	v_pk_add_f32 v[116:117], v[116:117], v[118:119]
	v_pk_add_f32 v[120:121], v[120:121], v[122:123]
	v_pk_add_f32 v[124:125], v[124:125], v[126:127]
	v_pk_add_f32 v[128:129], v[128:129], v[130:131]
	v_pk_add_f32 v[136:137], v[100:101], 0 op_sel_hi:[1,0]
	s_nop 0
	v_pk_add_f32 v[136:137], v[136:137], v[104:105]
	s_nop 0
	v_pk_add_f32 v[136:137], v[136:137], v[108:109]
	s_nop 0
	v_pk_add_f32 v[136:137], v[136:137], v[112:113]
	s_nop 0
	v_pk_add_f32 v[136:137], v[136:137], v[116:117]
	s_nop 0
	v_pk_add_f32 v[136:137], v[136:137], v[120:121]
	s_nop 0
	v_pk_add_f32 v[136:137], v[136:137], v[124:125]
	s_nop 0
	v_pk_add_f32 v[138:139], v[136:137], v[128:129]
	s_nop 0
	v_pk_mul_f32 v[138:139], v[138:139], s[98:99] op_sel_hi:[1,0]
	s_nop 0
	v_fma_f32 v132, -v138, v138, v139
	v_max_f32_e32 v132, 0, v132
	v_add_f32_e32 v132, 0x3727c5ac, v132
	v_cmp_gt_f32_e32 vcc, 0x800000, v132
	v_mul_f32_e32 v139, 0x4b800000, v132
	s_nop 0
	v_cndmask_b32_e32 v132, v132, v139, vcc
	v_rsq_f32_e32 v132, v132
	s_nop 0
	v_mul_f32_e32 v139, 0x45800000, v132
	v_cndmask_b32_e32 v139, v132, v139, vcc
	ds_write_b64 v217, v[138:139]

.LBB0_1097:
	v_lshrrev_b32_e32 v20, 1, v18
	v_and_b32_e32 v20, 24, v20
	v_and_b32_e32 v19, 15, v18
	v_lshlrev_b32_e32 v21, 1, v20
	v_lshlrev_b32_e32 v18, 2, v18
	s_lshl_b32 s3, s3, 5
	s_lshl_b32 s36, s27, 6
	v_lshl_or_b32 v21, v19, 6, v21
	s_lshl_b32 s27, s27, 13
	v_and_b32_e32 v18, 32, v18
	s_and_b32 s3, s3, 0x60
	s_add_i32 m0, s69, 0x18000
	v_lshl_add_u64 v[8:9], v[8:9], 0, s[22:23]
	v_bitop3_b32 v22, v21, s27, v18 bitop3:0xde
	s_lshl_b32 s27, s3, 7
	s_waitcnt vmcnt(4)
	s_barrier
	v_lshl_add_u64 v[6:7], v[6:7], 0, s[22:23]
	s_add_i32 m0, s69, 0x1a000
	s_add_i32 s73, s69, 0x8000
	s_add_i32 s75, s69, 0xa000
	v_lshl_add_u64 v[4:5], v[4:5], 0, s[22:23]
	s_mov_b32 m0, s73
	s_add_u32 s28, s54, 0x40080
	v_lshl_add_u64 v[2:3], v[2:3], 0, s[22:23]
	s_mov_b32 m0, s75
	s_addc_u32 s29, s55, 0
	s_add_i32 m0, s69, 0x1c000
	v_lshl_add_u64 v[2:3], s[28:29], 0, v[164:165]
	v_lshl_add_u64 v[2:3], s[28:29], 0, v[162:163]
	s_add_i32 m0, s69, 0x1e000
	v_or_b32_e32 v1, s36, v19
	v_lshlrev_b32_e32 v2, 13, v10
	v_and_b32_e32 v2, 0x7fffc000, v2
	v_lshl_add_u32 v2, v11, 10, v2
	s_addk_i32 s36, 0x80
	v_or_b32_e32 v2, v2, v12
	v_or_b32_e32 v172, s36, v19
	v_add_lshl_u32 v2, v2, v13, 1
	v_mov_b32_e32 v3, v0
	s_mov_b64 s[36:37], 0x40080
	v_lshl_add_u64 v[166:167], v[2:3], 0, s[36:37]
	v_lshlrev_b32_e32 v2, 13, v15
	v_and_b32_e32 v2, 0x7fffc000, v2
	v_lshl_add_u32 v2, v14, 10, v2
	v_or_b32_e32 v2, v2, v16
	s_waitcnt vmcnt(6)
	v_add_lshl_u32 v2, v2, v17, 1
	v_lshl_add_u64 v[168:169], v[2:3], 0, s[36:37]
	v_readlane_b32 s36, v252, 51
	v_bitop3_b32 v170, v21, s27, v18 bitop3:0xde
	v_or_b32_e32 v171, 32, v1
	v_or_b32_e32 v173, 32, v172
	s_and_b32 s29, s51, 0xffff
	s_mov_b32 s28, s50
	v_or_b32_e32 v174, s3, v20
	s_mov_b32 s76, 0
	v_add_u32_e32 v175, 0, v22
	s_mov_b32 s27, s36
	v_readlane_b32 s3, v254, 29
	s_barrier
	v_readlane_b32 s37, v252, 52

.LBB0_1169:
	s_add_u32 s58, s4, s36
	s_addc_u32 s59, s5, s37
	s_add_u32 s60, s4, s28
	s_addc_u32 s61, s5, s29
	v_readlane_b32 s4, v253, 39
	s_waitcnt vmcnt(0)
	v_mov_b32_e32 v19, v213
	v_readlane_b32 s5, v253, 40
	s_andn2_b64 vcc, exec, s[4:5]
	v_readfirstlane_b32 s76, v19
	s_cbranch_vccnz .LBB0_1223
	v_lshlrev_b32_e32 v2, 4, v19
	v_add_u32_e32 v1, 0x2000, v2
	v_ashrrev_i32_e32 v3, 31, v1
	v_lshrrev_b32_e32 v3, 22, v3
	v_add_u32_e32 v3, v1, v3
	v_ashrrev_i32_e32 v3, 10, v3
	v_mul_i32_i24_e32 v4, 0x400, v3
	v_sub_u32_e32 v1, v1, v4
	v_lshrrev_b32_e32 v4, 4, v1
	v_bitop3_b32 v4, v4, v1, 32 bitop3:0x6c
	v_ashrrev_i32_e32 v1, 31, v4
	v_lshrrev_b32_e32 v1, 26, v1
	v_add_u32_e32 v5, v4, v1
	v_lshlrev_b32_e32 v6, 3, v3
	v_ashrrev_i32_e32 v1, 6, v5
	v_and_b32_e32 v6, 0x7ffffff0, v6
	v_and_b32_e32 v5, 0xc0, v5
	v_add_u32_e32 v1, v1, v6
	v_lshlrev_b32_e32 v3, 5, v3
	v_sub_u32_e32 v4, v4, v5
	v_mul_lo_u32 v1, v1, s75
	v_and_b32_e32 v14, 32, v3
	v_ashrrev_i16_sdwa v4, v219, sext(v4) dst_sel:DWORD dst_unused:UNUSED_PAD src0_sel:DWORD src1_sel:BYTE_0
	v_or_b32_e32 v3, v1, v14
	v_bfe_i32 v15, v4, 0, 16
	v_add_lshl_u32 v200, v3, v15, 1
	v_bfe_i32 v3, v19, 27, 1
	v_lshrrev_b32_e32 v3, 22, v3
	v_add_u32_e32 v3, v2, v3
	v_and_b32_e32 v3, 0xfffffc00, v3
	v_sub_u32_e32 v2, v2, v3
	v_lshrrev_b32_e32 v3, 4, v2
	v_ashrrev_i32_e32 v5, 31, v19
	v_bitop3_b32 v2, v3, v2, 32 bitop3:0x6c
	v_lshrrev_b32_e32 v5, 26, v5
	v_ashrrev_i32_e32 v3, 31, v2
	v_add_u32_e32 v5, v19, v5
	v_lshrrev_b32_e32 v3, 26, v3
	v_ashrrev_i32_e32 v5, 6, v5
	v_add_u32_e32 v3, v2, v3
	v_lshlrev_b32_e32 v6, 3, v5
	v_ashrrev_i32_e32 v4, 6, v3
	v_and_b32_e32 v6, 0x7ffffff0, v6
	s_ashr_i32 s27, s76, 6
	s_lshl_b32 s77, s75, 9
	v_add_u32_e32 v4, v4, v6
	v_and_b32_e32 v3, 0xc0, v3
	v_readlane_b32 s36, v252, 51
	s_ashr_i32 s3, s76, 8
	s_lshl_b32 s4, s75, 8
	s_lshl_b32 s78, s27, 10
	v_mul_lo_u32 v16, v4, s75
	v_lshlrev_b32_e32 v4, 5, v5
	v_sub_u32_e32 v2, v2, v3
	s_mul_hi_i32 s29, s77, s36
	s_mul_i32 s36, s77, s36
	v_and_b32_e32 v17, 32, v4
	v_ashrrev_i16_sdwa v2, v219, sext(v2) dst_sel:DWORD dst_unused:UNUSED_PAD src0_sel:DWORD src1_sel:BYTE_0
	v_readlane_b32 s37, v252, 52
	s_add_u32 s36, s64, s36
	v_or_b32_e32 v4, v16, v17
	v_bfe_i32 v18, v2, 0, 16
	s_addc_u32 s37, s65, s29
	s_add_i32 s79, s78, 0
	v_add_lshl_u32 v202, v4, v18, 1
	v_readlane_b32 s28, v254, 29
	s_add_i32 m0, s79, 0x10000
	s_mul_i32 s28, s77, s28
	global_load_lds_dwordx4 v202, s[36:37]
	s_add_i32 m0, s79, 0x12000
	s_add_u32 s42, s62, s28
	global_load_lds_dwordx4 v200, s[36:37]
	s_addc_u32 s43, s63, 0
	s_mov_b32 m0, s79
	s_add_i32 s80, s79, 0x2000
	global_load_lds_dwordx4 v202, s[42:43]
	s_mov_b32 m0, s80
	s_add_u32 s28, s36, s4
	global_load_lds_dwordx4 v200, s[42:43]
	s_addc_u32 s29, s37, 0
	s_add_i32 m0, s79, 0x14000
	v_mov_b32_e32 v203, v0
	v_mov_b32_e32 v201, v0
	global_load_lds_dwordx4 v202, s[28:29]
	s_add_i32 m0, s79, 0x16000
	v_lshl_add_u64 v[10:11], s[28:29], 0, v[202:203]
	v_lshl_add_u64 v[12:13], s[28:29], 0, v[200:201]
	global_load_lds_dwordx4 v200, s[28:29]
	s_add_u32 s28, s42, s4
	s_addc_u32 s29, s43, 0
	s_add_i32 s81, s79, 0x4000
	s_mov_b32 m0, s81
	s_add_i32 s82, s79, 0x6000
	global_load_lds_dwordx4 v202, s[28:29]
	s_mov_b32 m0, s82
	s_mov_b32 s5, s39
	global_load_lds_dwordx4 v200, s[28:29]
	s_add_u32 s98, s36, s22
	s_addc_u32 s99, s37, s23
	s_add_i32 m0, s79, 0x18000
	s_nop 0
	global_load_lds_dwordx4 v202, s[98:99]
	s_add_i32 m0, s79, 0x1a000
	s_nop 0
	global_load_lds_dwordx4 v200, s[98:99]
	s_add_u32 s100, s42, s22
	s_addc_u32 s101, s43, s23
	s_add_i32 m0, s79, 0x8000
	s_nop 0
	global_load_lds_dwordx4 v202, s[100:101]
	s_add_i32 m0, s79, 0xa000
	s_nop 0
	global_load_lds_dwordx4 v200, s[100:101]
	s_add_u32 s98, s98, s4
	s_addc_u32 s99, s99, 0
	s_add_i32 m0, s79, 0x1c000
	s_nop 0
	global_load_lds_dwordx4 v202, s[98:99]
	s_add_i32 m0, s79, 0x1e000
	s_nop 0
	global_load_lds_dwordx4 v200, s[98:99]
	s_cmp_eq_u64 s[50:51], 0
	s_cbranch_scc1 .Lstat_done_4
	s_mov_b64 s[100:101], exec
	v_readlane_b32 s98, v254, 59
	v_readlane_b32 s99, v254, 60
	s_and_b64 s[98:99], s[100:101], s[98:99]
	s_mov_b64 exec, s[98:99]
	s_cbranch_execz .Lstat_skip_4
	v_lshl_add_u64 v[134:135], s[50:51], 0, v[198:199]
	global_load_dwordx4 v[100:103], v[134:135], off
	global_load_dwordx4 v[104:107], v[134:135], off offset:16
	global_load_dwordx4 v[108:111], v[134:135], off offset:32
	global_load_dwordx4 v[112:115], v[134:135], off offset:48
	global_load_dwordx4 v[116:119], v[134:135], off offset:64
	global_load_dwordx4 v[120:123], v[134:135], off offset:80
	global_load_dwordx4 v[124:127], v[134:135], off offset:96
	global_load_dwordx4 v[128:131], v[134:135], off offset:112
	s_mov_b32 s98, 0x3a800000
	s_waitcnt vmcnt(0) lgkmcnt(0)
	v_pk_add_f32 v[100:101], v[100:101], v[102:103]
	v_pk_add_f32 v[104:105], v[104:105], v[106:107]
	v_pk_add_f32 v[108:109], v[108:109], v[110:111]
	v_pk_add_f32 v[112:113], v[112:113], v[114:115]
	v_pk_add_f32 v[116:117], v[116:117], v[118:119]
	v_pk_add_f32 v[120:121], v[120:121], v[122:123]
	v_pk_add_f32 v[124:125], v[124:125], v[126:127]
	v_pk_add_f32 v[128:129], v[128:129], v[130:131]
	v_pk_add_f32 v[136:137], v[100:101], 0 op_sel_hi:[1,0]
	s_nop 0
	v_pk_add_f32 v[136:137], v[136:137], v[104:105]
	s_nop 0
	v_pk_add_f32 v[136:137], v[136:137], v[108:109]
	s_nop 0
	v_pk_add_f32 v[136:137], v[136:137], v[112:113]
	s_nop 0
	v_pk_add_f32 v[136:137], v[136:137], v[116:117]
	s_nop 0
	v_pk_add_f32 v[136:137], v[136:137], v[120:121]
	s_nop 0
	v_pk_add_f32 v[136:137], v[136:137], v[124:125]
	s_nop 0
	v_pk_add_f32 v[138:139], v[136:137], v[128:129]
	s_nop 0
	v_pk_mul_f32 v[138:139], v[138:139], s[98:99] op_sel_hi:[1,0]
	s_nop 0
	v_fma_f32 v132, -v138, v138, v139
	v_max_f32_e32 v132, 0, v132
	v_add_f32_e32 v132, 0x3727c5ac, v132
	v_cmp_gt_f32_e32 vcc, 0x800000, v132
	v_mul_f32_e32 v139, 0x4b800000, v132
	s_nop 0
	v_cndmask_b32_e32 v132, v132, v139, vcc
	v_rsq_f32_e32 v132, v132
	s_nop 0
	v_mul_f32_e32 v139, 0x45800000, v132
	v_cndmask_b32_e32 v139, v132, v139, vcc
	ds_write_b64 v217, v[138:139]

.LBB0_1172:
	s_add_i32 m0, s79, 0x18000
	v_lshl_add_u64 v[2:3], v[2:3], 0, s[22:23]
	s_waitcnt vmcnt(4)
	s_barrier
	v_lshl_add_u64 v[2:3], v[4:5], 0, s[22:23]
	s_add_i32 m0, s79, 0x1a000
	s_add_i32 s86, s79, 0x8000
	v_lshl_add_u64 v[2:3], v[6:7], 0, s[22:23]
	s_mov_b32 m0, s86
	s_add_i32 s87, s79, 0xa000
	v_lshl_add_u64 v[2:3], v[8:9], 0, s[22:23]
	s_mov_b32 m0, s87
	v_bfe_u32 v20, v19, 4, 2
	s_add_i32 m0, s79, 0x1c000
	v_lshl_add_u64 v[2:3], v[10:11], 0, s[22:23]
	v_lshl_add_u64 v[2:3], v[12:13], 0, s[22:23]
	s_add_i32 m0, s79, 0x1e000
	v_and_b32_e32 v221, 15, v19
	v_lshlrev_b32_e32 v22, 4, v20
	v_lshlrev_b32_e32 v19, 2, v19
	s_and_b32 s83, s27, 3
	s_lshl_b32 s85, s3, 6
	v_lshl_or_b32 v22, v221, 6, v22
	s_lshl_b32 s3, s3, 13
	v_and_b32_e32 v19, 32, v19
	v_bitop3_b32 v23, v22, s3, v19 bitop3:0xde
	s_lshl_b32 s3, s83, 12
	v_add_u32_e32 v1, v1, v14
	v_bitop3_b32 v223, v22, s3, v19 bitop3:0xde
	s_waitcnt vmcnt(6)
	s_add_i32 s3, s85, 0x80
	v_add_lshl_u32 v2, v1, v15, 1
	v_mov_b32_e32 v3, v0
	v_add_u32_e32 v1, v16, v17
	v_readlane_b32 s66, v252, 51
	s_lshr_b32 s84, s75, 6
	v_or_b32_e32 v222, s85, v221
	v_lshlrev_b32_e32 v21, 3, v20
	v_or_b32_e32 v228, s3, v221
	v_lshl_add_u64 v[204:205], s[4:5], 0, v[2:3]
	v_add_lshl_u32 v2, v1, v18, 1
	v_readlane_b32 s67, v252, 52
	v_lshl_or_b32 v224, s83, 5, v21
	v_or_b32_e32 v225, 0x80, v221
	v_or_b32_e32 v226, 0xa0, v221
	s_add_i32 s88, s84, -2
	s_mov_b32 s89, 0
	v_cmp_eq_u32_e64 s[40:41], 0, v20
	v_or_b32_e32 v227, 32, v222
	v_or_b32_e32 v229, 32, v228
	s_and_b32 s29, s59, 0xffff
	s_mov_b32 s28, s58
	v_lshl_add_u64 v[206:207], s[4:5], 0, v[2:3]
	v_add_u32_e32 v230, 0, v23
	s_mov_b32 s38, s66
	v_readlane_b32 s3, v254, 29
	s_mov_b64 s[66:67], s[42:43]
	s_barrier
	s_branch .LBB0_1174
